# ssm_b: hoist loop-invariant g2 gain loads out of the chunk loop (as in ssm_a)
# speedup vs baseline: 1.0170x; 1.0113x over previous
.LBB0_218:
	s_lshl_b32 s46, s26, 2
	s_lshl_b32 s3, s26, 4
	s_lshl_b32 s0, s86, 13
	s_lshl_b32 s1, s87, 9
	s_ashr_i32 s47, s46, 31
	s_or_b32 s51, s0, s1
	s_lshl_b32 s88, s2, 1
	s_lshl_b64 s[0:1], s[46:47], 14
	s_or_b32 s42, s46, 1
	s_or_b32 s44, s46, 2
	s_or_b32 s46, s46, 3
	v_add_u32_e32 v46, s3, v116
	v_lshl_add_u64 v[82:83], v[56:57], 0, s[88:89]
	s_lshl_b64 s[52:53], s[22:23], 1
	s_ashr_i32 s43, s42, 31
	s_ashr_i32 s45, s44, 31
	s_ashr_i32 s47, s46, 31
	s_lshl_b32 s88, s2, 2
	v_ashrrev_i32_e32 v47, 31, v46
	v_mov_b32_e32 v80, v79
	v_mov_b32_e32 v81, v79
	s_add_i32 s50, s3, 0x4000
	v_lshl_add_u64 v[84:85], v[60:61], 0, s[52:53]
	v_lshl_add_u64 v[86:87], v[62:63], 0, s[52:53]
	s_lshl_b64 s[40:41], s[68:69], 8
	s_lshl_b64 s[42:43], s[42:43], 14
	s_lshl_b64 s[44:45], s[44:45], 14
	s_lshl_b64 s[46:47], s[46:47], 14
	v_lshl_add_u64 v[88:89], v[64:65], 0, s[88:89]
	s_and_b64 vcc, exec, s[36:37]
	s_cbranch_vccz .Lssmb_nog2
	global_load_dwordx4 v[240:243], v[88:89], off offset:16
	global_load_dwordx4 v[244:247], v[88:89], off
.Lssmb_nog2:
	v_lshl_add_u64 v[90:91], s[22:23], 2, v[66:67]
	v_mov_b32_e32 v92, v78
	v_mov_b32_e32 v93, v78
	v_pk_mov_b32 v[94:95], v[78:79], v[78:79] op_sel:[1,0]
	v_mov_b32_e32 v96, v79
	v_or_b32_e32 v71, s51, v55
	v_lshlrev_b64 v[98:99], 11, v[46:47]
	v_lshl_add_u64 v[100:101], v[68:69], 0, s[52:53]
	s_mov_b32 s22, 0
	s_branch .LBB0_220

.LBB0_220:
	s_lshl_b32 s2, s22, 6
	s_andn2_b64 vcc, exec, s[36:37]
	s_add_i32 s2, s51, s2
	s_cbranch_vccnz .LBB0_224
	s_barrier
	v_lshlrev_b32_e32 v0, 16, v2
	s_cmp_eq_u32 s22, 7
	s_waitcnt vmcnt(0)
	v_mul_f32_e32 v0, v244, v0
	v_and_b32_e32 v50, 0xffff0000, v2
	v_mul_f32_e32 v50, v245, v50
	v_cvt_pk_bf16_f32 v50, v0, v50
	v_lshlrev_b32_e32 v0, 16, v3
	v_and_b32_e32 v51, 0xffff0000, v3
	v_mul_f32_e32 v0, v246, v0
	v_mul_f32_e32 v51, v247, v51
	v_cvt_pk_bf16_f32 v51, v0, v51
	v_lshlrev_b32_e32 v0, 16, v4
	v_mul_f32_e32 v0, v240, v0
	v_and_b32_e32 v46, 0xffff0000, v4
	v_mul_f32_e32 v46, v241, v46
	v_cvt_pk_bf16_f32 v52, v0, v46
	v_lshlrev_b32_e32 v0, 16, v5
	v_and_b32_e32 v46, 0xffff0000, v5
	v_mul_f32_e32 v0, v242, v0
	v_mul_f32_e32 v46, v243, v46
	v_cvt_pk_bf16_f32 v53, v0, v46
	ds_write_b128 v117, v[50:53]
	v_lshlrev_b32_e32 v0, 16, v6
	s_waitcnt vmcnt(0)
	v_mul_f32_e32 v0, v244, v0
	v_and_b32_e32 v50, 0xffff0000, v6
	v_mul_f32_e32 v50, v245, v50
	v_cvt_pk_bf16_f32 v50, v0, v50
	v_lshlrev_b32_e32 v0, 16, v7
	v_and_b32_e32 v51, 0xffff0000, v7
	v_mul_f32_e32 v0, v246, v0
	v_mul_f32_e32 v51, v247, v51
	v_cvt_pk_bf16_f32 v51, v0, v51
	v_lshlrev_b32_e32 v0, 16, v8
	v_mul_f32_e32 v0, v240, v0
	v_and_b32_e32 v46, 0xffff0000, v8
	v_mul_f32_e32 v46, v241, v46
	v_cvt_pk_bf16_f32 v52, v0, v46
	v_lshlrev_b32_e32 v0, 16, v9
	v_and_b32_e32 v46, 0xffff0000, v9
	v_mul_f32_e32 v0, v242, v0
	v_mul_f32_e32 v46, v243, v46
	v_cvt_pk_bf16_f32 v53, v0, v46
	ds_write_b128 v118, v[50:53]
	s_cbranch_scc1 .LBB0_223
	s_add_i32 s3, s2, 64
	v_add_u32_e32 v2, s3, v59
	v_add_u32_e32 v4, s3, v110
	v_ashrrev_i32_e32 v3, 31, v2
	v_ashrrev_i32_e32 v5, 31, v4
	v_lshlrev_b64 v[2:3], 11, v[2:3]
	v_lshlrev_b64 v[4:5], 11, v[4:5]
	v_lshl_add_u64 v[2:3], v[82:83], 0, v[2:3]
	v_lshl_add_u64 v[6:7], v[82:83], 0, v[4:5]
	global_load_dwordx4 v[2:5], v[2:3], off
	s_nop 0
	global_load_dwordx4 v[6:9], v[6:7], off
